# phase 0 load balance: the SSM-parameter prep items (double-precision exp/sincos) run on blocks 240-255 instead of blocks 0-15, which already carry the extra row-conversion iteration and the sample-K i
# speedup vs baseline: 1.0628x; 1.0015x over previous
.LBB0_98:
	v_writelane_b32 v237, s36, 22
	s_cmpk_lt_u32 s2, 0xf0
	s_nop 0
	v_writelane_b32 v237, s37, 23
	v_writelane_b32 v237, s38, 24
	v_writelane_b32 v237, s39, 25
	v_writelane_b32 v237, s40, 26
	v_writelane_b32 v237, s41, 27
	v_writelane_b32 v237, s42, 28
	v_writelane_b32 v237, s43, 29
	v_writelane_b32 v237, s44, 30
	v_writelane_b32 v237, s45, 31
	v_writelane_b32 v237, s46, 32
	v_writelane_b32 v237, s47, 33
	v_writelane_b32 v237, s48, 34
	v_writelane_b32 v237, s49, 35
	v_writelane_b32 v237, s50, 36
	v_writelane_b32 v237, s51, 37
	s_cbranch_scc1 .LBB0_111
	s_mov_b32 s28, 0xeff8d898
	s_add_u32 s20, s86, 0xf600000
	v_lshlrev_b32_e32 v9, 4, v22
	s_mov_b32 s22, 0x652b82fe
	s_mov_b32 s24, 0xfee00000
	s_mov_b32 s26, 0x35793c76
	s_mov_b32 s29, 0x3e21eed8
	s_mov_b32 s30, 0x13a86d09
	v_mov_b32_e32 v4, 0x67f544e4
	v_mov_b32_e32 v6, 0xb7789f5c
	s_mov_b32 s34, 0xa556c734
	s_mov_b32 s36, 0x1a01a01a
	v_mov_b32_e32 v11, 0x3f2a01a0
	v_mov_b32_e32 v14, 0x16c16c17
	s_mov_b32 s38, 0x11111111
	s_mov_b32 s40, 0x55555555
	v_mov_b32_e32 v19, 0x3fc55555
	s_mov_b32 s42, 0x6dc9c883
	s_mov_b32 s8, 0x54442d18
	s_mov_b32 s10, 0x33145c07
	s_mov_b32 s12, 0x46814157
	v_mov_b32_e32 v26, 0xe733b81f
	s_mov_b32 s14, 0xa4020225
	s_addc_u32 s21, s87, 0
	s_mov_b32 s23, 0x3ff71547
	s_mov_b32 s25, 0xbfe62e42
	s_mov_b32 s27, 0xbdea39ef
	s_mov_b32 s31, 0x3de61246
	v_mov_b64_e32 v[2:3], s[28:29]
	v_mov_b32_e32 v5, 0x3e5ae645
	v_mov_b32_e32 v7, 0x3e927e4f
	s_mov_b32 s35, 0x3ec71de3
	s_mov_b32 s37, 0x3efa01a0
	v_mov_b32_e32 v8, 0x1a01a01a
	v_mov_b32_e32 v12, 0x1a01a01a
	v_mov_b32_e32 v13, v11
	v_mov_b32_e32 v15, 0x3f56c16c
	s_mov_b32 s39, 0x3f811111
	s_mov_b32 s41, 0x3fa55555
	v_mov_b32_e32 v16, 0x55555555
	v_mov_b32_e32 v20, 0x55555555
	v_mov_b32_e32 v21, v19
	s_movk_i32 s3, 0xffe0
	v_mov_b32_e32 v69, 0x3ff00000
	v_mov_b32_e32 v22, 0
	s_mov_b32 s43, 0x3fe45f30
	s_mov_b32 s9, 0xbff921fb
	s_mov_b32 s11, 0xbc91a626
	v_mov_b32_e32 v24, 0x7030ad4a
	v_mov_b32_e32 v25, 0x3ce952c7
	s_mov_b32 s13, 0xbc62f49b
	v_mov_b32_e32 v27, 0xbd6ae7f3
	v_mov_b32_e32 v29, 0xbe5ae645
	v_mov_b32_e32 v28, v4
	v_mov_b32_e32 v31, 0xbf2a01a0
	v_mov_b32_e32 v30, 0x1a01a01a
	v_mov_b32_e32 v33, 0xbfc55555
	v_mov_b32_e32 v32, 0x55555555
	v_mov_b32_e32 v34, 0x63b97d97
	v_mov_b32_e32 v35, 0xbca68278
	s_mov_b32 s15, 0x3c1e542b
	v_mov_b32_e32 v37, 0x3d2ae7f3
	v_mov_b32_e32 v36, v26
	v_mov_b32_e32 v38, 0xa8c07c9d
	v_mov_b32_e32 v39, 0xbda93974
	v_mov_b32_e32 v41, 0xbe927e4f
	v_lshlrev_b32_e32 v70, 1, v9
	v_mov_b32_e32 v40, v6
	v_mov_b32_e32 v43, 0xbf56c16c
	v_mov_b32_e32 v42, v14
	v_mov_b32_e32 v44, 0xeff8d898
	v_mov_b32_e32 v45, 0x3e21eed8
	v_mov_b32_e32 v46, 0xa556c734
	v_mov_b32_e32 v47, 0x3ec71de3
	v_mov_b32_e32 v9, 0x3efa01a0
	v_mov_b32_e32 v48, 0x11111111
	v_mov_b32_e32 v49, 0x3f811111
	v_mov_b32_e32 v17, 0x3fa55555
	s_and_b32 s33, s2, 15
